# phase-0 input RMS norm: two-rows-ahead load prefetch with three rotating register sets and counted vmcnt
# speedup vs baseline: 1.0064x; 1.0064x over previous
; #define GAS __attribute__((address_space(1)))
; template <bool FIRST>
; __device__ __forceinline__ void norm_phase(const float* xp, const float* xs, float* out, unsigned char* ws, int mode, const float* gain, int gw, int NGW, int lane) {
;     asm volatile("" : "+v"(lane));
;     bf16_t* xb = (bf16_t*)(ws + WS_XB);
;     float* ss1 = (float*)(ws + WS_SS1);
;     for (int m = gw; m < M; m += NGW) {
;         f32x4 v[4]; float s = 0.f;
;         if (FIRST) {
;             const float* src = (m < SEQ ? xp + (size_t)m * D : xs + (size_t)(m - SEQ) * D);
; #pragma unroll
;             for (int j = 0; j < 4; ++j) v[j] = *((const GAS f32x4*)src + lane + 64 * j);
.LBB0_90:
	s_cmp_lt_i32 s68, 0xc000
	v_mov_b32_e32 v0, v152
	s_cselect_b64 s[40:41], -1, 0
	s_cmp_gt_i32 s68, 0xbfff
	v_mbcnt_lo_u32_b32 v155, -1, 0
	s_cbranch_scc1 .LBB0_97
	v_mbcnt_hi_u32_b32 v2, -1, v155
	v_and_b32_e32 v3, 64, v2
	v_add_u32_e32 v3, 64, v3
	v_xor_b32_e32 v4, 1, v2
	v_cmp_lt_i32_e32 vcc, v4, v3
	v_xor_b32_e32 v5, 2, v2
	v_xor_b32_e32 v6, 4, v2
	v_cndmask_b32_e32 v4, v2, v4, vcc
	v_cmp_lt_i32_e32 vcc, v5, v3
	v_xor_b32_e32 v7, 8, v2
	v_xor_b32_e32 v8, 16, v2
	v_cndmask_b32_e32 v5, v2, v5, vcc
	v_cmp_lt_i32_e32 vcc, v6, v3
	v_xor_b32_e32 v9, 32, v2
	v_ashrrev_i32_e32 v1, 31, v0
	v_cndmask_b32_e32 v6, v2, v6, vcc
	v_cmp_lt_i32_e32 vcc, v7, v3
	s_mov_b64 s[2:3], 0x5400000
	s_ashr_i32 s69, s68, 31
	v_cndmask_b32_e32 v7, v2, v7, vcc
	v_cmp_lt_i32_e32 vcc, v8, v3
	s_ashr_i32 s71, s70, 31
	s_mov_b32 s1, 0
	v_cndmask_b32_e32 v8, v2, v8, vcc
	v_cmp_lt_i32_e32 vcc, v9, v3
	v_lshlrev_b32_e32 v4, 2, v4
	v_lshlrev_b32_e32 v5, 2, v5
	v_cndmask_b32_e32 v2, v2, v9, vcc
	v_lshlrev_b32_e32 v9, 2, v2
	v_lshl_add_u64 v[2:3], v[0:1], 3, s[72:73]
	v_lshl_add_u64 v[2:3], v[2:3], 0, s[2:3]
	s_lshl_b64 s[2:3], s[68:69], 12
	s_add_u32 s2, s52, s2
	v_lshlrev_b32_e32 v6, 2, v6
	v_lshlrev_b32_e32 v7, 2, v7
	v_lshlrev_b32_e32 v8, 2, v8
	v_cmp_eq_u32_e32 vcc, 0, v0
	s_addc_u32 s3, s53, s3
	s_lshl_b64 s[4:5], s[70:71], 12
	v_mov_b32_e32 v10, 0
	s_mov_b64 s[6:7], s[68:69]
	s_waitcnt lgkmcnt(0)
	s_cmpk_lt_i32 s6, 0x4000
	s_cselect_b32 s94, s52, s54
	s_cselect_b32 s95, s53, s55
	s_cselect_b32 s93, 0, 0x4000
	s_sub_i32 s93, s6, s93
	s_lshl_b32 s93, s93, 12
	s_add_u32 s94, s94, s93
	s_addc_u32 s95, s95, 0
	v_lshl_add_u64 v[28:29], v[0:1], 4, s[94:95]
	global_load_dwordx4 v[12:15], v[28:29], off
	global_load_dwordx4 v[16:19], v[28:29], off offset:1024
	global_load_dwordx4 v[20:23], v[28:29], off offset:2048
	global_load_dwordx4 v[24:27], v[28:29], off offset:3072
	s_add_i32 s92, s6, s70
	s_cmp_lt_i32 s92, 0xc000
	s_cbranch_scc0 .Lnp_p1skip
	s_cmpk_lt_i32 s92, 0x4000
	s_cselect_b32 s94, s52, s54
	s_cselect_b32 s95, s53, s55
	s_cselect_b32 s93, 0, 0x4000
	s_sub_i32 s93, s92, s93
	s_lshl_b32 s93, s93, 12
	s_add_u32 s94, s94, s93
	s_addc_u32 s95, s95, 0
	v_lshl_add_u64 v[28:29], v[0:1], 4, s[94:95]
	global_load_dwordx4 v[56:59], v[28:29], off
	global_load_dwordx4 v[60:63], v[28:29], off offset:1024
	global_load_dwordx4 v[64:67], v[28:29], off offset:2048
	global_load_dwordx4 v[68:71], v[28:29], off offset:3072
.Lnp_p1skip:
	s_add_i32 s92, s6, s70
	s_add_i32 s92, s92, s70
	s_cmp_lt_i32 s92, 0xc000
	s_cbranch_scc0 .Lnp_skip_a0
	s_cmpk_lt_i32 s92, 0x4000
	s_cselect_b32 s94, s52, s54
	s_cselect_b32 s95, s53, s55
	s_cselect_b32 s93, 0, 0x4000
	s_sub_i32 s93, s92, s93
	s_lshl_b32 s93, s93, 12
	s_add_u32 s94, s94, s93
	s_addc_u32 s95, s95, 0
	v_lshl_add_u64 v[28:29], v[0:1], 4, s[94:95]
	global_load_dwordx4 v[72:75], v[28:29], off
	global_load_dwordx4 v[76:79], v[28:29], off offset:1024
	global_load_dwordx4 v[80:83], v[28:29], off offset:2048
	global_load_dwordx4 v[84:87], v[28:29], off offset:3072
	s_waitcnt vmcnt(8)
	s_branch .Lnp_proc_a0

; #define GAS __attribute__((address_space(1)))
; __device__ __forceinline__ unsigned cvt_pk_bf16(float lo, float hi) { f32x2_t v = {lo, hi}; bf16x2_t b = __builtin_convertvector(v, bf16x2_t); return __builtin_bit_cast(unsigned, b); }
; template <bool FIRST>
; __device__ __forceinline__ void norm_phase(const float* xp, const float* xs, float* out, unsigned char* ws, int mode, const float* gain, int gw, int NGW, int lane) {
;     ...
;     for (int m = gw; m < M; m += NGW) {
;         f32x4 v[4]; float s = 0.f;
;         if (FIRST) {
;             const float* src = (m < SEQ ? xp + (size_t)m * D : xs + (size_t)(m - SEQ) * D);
; #pragma unroll
;             for (int j = 0; j < 4; ++j) v[j] = *((const GAS f32x4*)src + lane + 64 * j);
;         } else {
; #pragma unroll
;             for (int j = 0; j < 4; ++j) { const u32x2 w = *((const GAS u32x2*)(xb + (size_t)m * D) + lane + 64 * j);
;                 v[j] = (f32x4){__uint_as_float(w.x << 16), __uint_as_float(w.x & 0xffff0000u), __uint_as_float(w.y << 16), __uint_as_float(w.y & 0xffff0000u)}; }
;         }
; #pragma unroll
;         for (int j = 0; j < 4; ++j) s += (v[j][0] * v[j][0] + v[j][1] * v[j][1]) + (v[j][2] * v[j][2] + v[j][3] * v[j][3]);
;         s = wave_sum(s);
;         if (!FIRST) {
;             const float rs = __builtin_amdgcn_rsqf(s * (1.0f / 1024.0f) + EPS); float s2 = 0.f;
; #pragma unroll
;             for (int j = 0; j < 4; ++j) { const f32x4 gg = *((const GAS f32x4*)gain + lane + 64 * j); v[j] = v[j] * rs * gg; s2 += (v[j][0] * v[j][0] + v[j][1] * v[j][1]) + (v[j][2] * v[j][2] + v[j][3] * v[j][3]); }
;             s = wave_sum(s2);
;         }
;         if (mode == 2) {
; #pragma unroll
;             for (int j = 0; j < 4; ++j) *((GAS f32x4*)(out + (size_t)m * D) + lane + 64 * j) = v[j];
;         } else {
; #pragma unroll
;             for (int j = 0; j < 4; ++j) { u32x2 w; w.x = cvt_pk_bf16(v[j][0], v[j][1]); w.y = cvt_pk_bf16(v[j][2], v[j][3]); *((GAS u32x2*)(xb + (size_t)m * D) + lane + 64 * j) = w; }
;             if (lane == 0) ss1[m] = s;
.Lnp_proc_a0:
	v_mul_f32_e32 v11, v13, v13
	v_mul_f32_e32 v28, v15, v15
	v_mul_f32_e32 v29, v17, v17
	v_mul_f32_e32 v30, v19, v19
	v_mul_f32_e32 v31, v21, v21
	v_mul_f32_e32 v32, v23, v23
	v_fmac_f32_e32 v11, v12, v12
	v_fmac_f32_e32 v28, v14, v14
	v_fmac_f32_e32 v29, v16, v16
	v_fmac_f32_e32 v30, v18, v18
	v_mul_f32_e32 v33, v25, v25
	v_mul_f32_e32 v34, v27, v27
	v_fmac_f32_e32 v31, v20, v20
	v_fmac_f32_e32 v32, v22, v22
	v_add_f32_e32 v11, v11, v28
	v_add_f32_e32 v28, v29, v30
	v_fmac_f32_e32 v33, v24, v24
	v_fmac_f32_e32 v34, v26, v26
	v_add_f32_e32 v29, v31, v32
	v_add_f32_e32 v11, v11, v28
	v_add_f32_e32 v30, v33, v34
	v_add_f32_e32 v11, v11, v29
	v_add_f32_e32 v11, v11, v30
	ds_bpermute_b32 v28, v4, v11
	v_cvt_pk_bf16_f32 v88, v12, v13
	v_cvt_pk_bf16_f32 v89, v14, v15
	v_cvt_pk_bf16_f32 v90, v16, v17
	v_cvt_pk_bf16_f32 v91, v18, v19
	v_cvt_pk_bf16_f32 v92, v20, v21
	v_cvt_pk_bf16_f32 v93, v22, v23
	v_cvt_pk_bf16_f32 v94, v24, v25
	v_cvt_pk_bf16_f32 v95, v26, v27
	s_lshl_b32 s10, s6, 11
	s_mov_b32 s11, 0
	v_lshl_add_u64 v[30:31], v[2:3], 0, s[10:11]
	global_store_dwordx2 v[30:31], v[88:89], off
	global_store_dwordx2 v[30:31], v[90:91], off offset:512
	global_store_dwordx2 v[30:31], v[92:93], off offset:1024
	global_store_dwordx2 v[30:31], v[94:95], off offset:1536
	s_waitcnt lgkmcnt(0)
	v_add_f32_e32 v11, v11, v28
	ds_bpermute_b32 v28, v5, v11
	s_waitcnt lgkmcnt(0)
	v_add_f32_e32 v11, v11, v28
	ds_bpermute_b32 v28, v6, v11
	s_waitcnt lgkmcnt(0)
	v_add_f32_e32 v11, v11, v28
	ds_bpermute_b32 v28, v7, v11
	s_waitcnt lgkmcnt(0)
	v_add_f32_e32 v11, v11, v28
	ds_bpermute_b32 v28, v8, v11
	s_waitcnt lgkmcnt(0)
	v_add_f32_e32 v11, v11, v28
	ds_bpermute_b32 v28, v9, v11
	s_lshl_b32 s8, s6, 2
	s_add_u32 s8, s72, s8
	s_addc_u32 s9, s73, 0
	s_and_saveexec_b64 s[10:11], vcc
	s_waitcnt lgkmcnt(0)
	v_add_f32_e32 v11, v11, v28
	global_store_dword v10, v11, s[8:9]
	s_or_b64 exec, exec, s[10:11]
	s_add_i32 s6, s6, s70
	s_cmp_lt_i32 s6, 0xc000
	s_cbranch_scc0 .Lnp_done
	s_add_i32 s92, s6, s70
	s_add_i32 s92, s92, s70
	s_cmp_lt_i32 s92, 0xc000
	s_cbranch_scc0 .Lnp_skip_a1
	s_cmpk_lt_i32 s92, 0x4000
	s_cselect_b32 s94, s52, s54
	s_cselect_b32 s95, s53, s55
	s_cselect_b32 s93, 0, 0x4000
	s_sub_i32 s93, s92, s93
	s_lshl_b32 s93, s93, 12
	s_add_u32 s94, s94, s93
	s_addc_u32 s95, s95, 0
	v_lshl_add_u64 v[28:29], v[0:1], 4, s[94:95]
	global_load_dwordx4 v[12:15], v[28:29], off
	global_load_dwordx4 v[16:19], v[28:29], off offset:1024
	global_load_dwordx4 v[20:23], v[28:29], off offset:2048
	global_load_dwordx4 v[24:27], v[28:29], off offset:3072
	s_waitcnt vmcnt(13)
	s_branch .Lnp_proc_a1

; #define GAS __attribute__((address_space(1)))
; __device__ __forceinline__ unsigned cvt_pk_bf16(float lo, float hi) { f32x2_t v = {lo, hi}; bf16x2_t b = __builtin_convertvector(v, bf16x2_t); return __builtin_bit_cast(unsigned, b); }
; template <bool FIRST>
; __device__ __forceinline__ void norm_phase(const float* xp, const float* xs, float* out, unsigned char* ws, int mode, const float* gain, int gw, int NGW, int lane) {
;     ...
; #pragma unroll
;         for (int j = 0; j < 4; ++j) s += (v[j][0] * v[j][0] + v[j][1] * v[j][1]) + (v[j][2] * v[j][2] + v[j][3] * v[j][3]);
;         s = wave_sum(s);
;         if (!FIRST) {
;             const float rs = __builtin_amdgcn_rsqf(s * (1.0f / 1024.0f) + EPS); float s2 = 0.f;
; #pragma unroll
;             for (int j = 0; j < 4; ++j) { const f32x4 gg = *((const GAS f32x4*)gain + lane + 64 * j); v[j] = v[j] * rs * gg; s2 += (v[j][0] * v[j][0] + v[j][1] * v[j][1]) + (v[j][2] * v[j][2] + v[j][3] * v[j][3]); }
;             s = wave_sum(s2);
;         }
;         if (mode == 2) {
; #pragma unroll
;             for (int j = 0; j < 4; ++j) *((GAS f32x4*)(out + (size_t)m * D) + lane + 64 * j) = v[j];
;         } else {
; #pragma unroll
;             for (int j = 0; j < 4; ++j) { u32x2 w; w.x = cvt_pk_bf16(v[j][0], v[j][1]); w.y = cvt_pk_bf16(v[j][2], v[j][3]); *((GAS u32x2*)(xb + (size_t)m * D) + lane + 64 * j) = w; }
;             if (lane == 0) ss1[m] = s;
.Lnp_proc_a1:
	v_mul_f32_e32 v11, v57, v57
	v_mul_f32_e32 v28, v59, v59
	v_mul_f32_e32 v29, v61, v61
	v_mul_f32_e32 v30, v63, v63
	v_mul_f32_e32 v31, v65, v65
	v_mul_f32_e32 v32, v67, v67
	v_fmac_f32_e32 v11, v56, v56
	v_fmac_f32_e32 v28, v58, v58
	v_fmac_f32_e32 v29, v60, v60
	v_fmac_f32_e32 v30, v62, v62
	v_mul_f32_e32 v33, v69, v69
	v_mul_f32_e32 v34, v71, v71
	v_fmac_f32_e32 v31, v64, v64
	v_fmac_f32_e32 v32, v66, v66
	v_add_f32_e32 v11, v11, v28
	v_add_f32_e32 v28, v29, v30
	v_fmac_f32_e32 v33, v68, v68
	v_fmac_f32_e32 v34, v70, v70
	v_add_f32_e32 v29, v31, v32
	v_add_f32_e32 v11, v11, v28
	v_add_f32_e32 v30, v33, v34
	v_add_f32_e32 v11, v11, v29
	v_add_f32_e32 v11, v11, v30
	ds_bpermute_b32 v28, v4, v11
	v_cvt_pk_bf16_f32 v88, v56, v57
	v_cvt_pk_bf16_f32 v89, v58, v59
	v_cvt_pk_bf16_f32 v90, v60, v61
	v_cvt_pk_bf16_f32 v91, v62, v63
	v_cvt_pk_bf16_f32 v92, v64, v65
	v_cvt_pk_bf16_f32 v93, v66, v67
	v_cvt_pk_bf16_f32 v94, v68, v69
	v_cvt_pk_bf16_f32 v95, v70, v71
	s_lshl_b32 s10, s6, 11
	s_mov_b32 s11, 0
	v_lshl_add_u64 v[30:31], v[2:3], 0, s[10:11]
	global_store_dwordx2 v[30:31], v[88:89], off
	global_store_dwordx2 v[30:31], v[90:91], off offset:512
	global_store_dwordx2 v[30:31], v[92:93], off offset:1024
	global_store_dwordx2 v[30:31], v[94:95], off offset:1536
	s_waitcnt lgkmcnt(0)
	v_add_f32_e32 v11, v11, v28
	ds_bpermute_b32 v28, v5, v11
	s_waitcnt lgkmcnt(0)
	v_add_f32_e32 v11, v11, v28
	ds_bpermute_b32 v28, v6, v11
	s_waitcnt lgkmcnt(0)
	v_add_f32_e32 v11, v11, v28
	ds_bpermute_b32 v28, v7, v11
	s_waitcnt lgkmcnt(0)
	v_add_f32_e32 v11, v11, v28
	ds_bpermute_b32 v28, v8, v11
	s_waitcnt lgkmcnt(0)
	v_add_f32_e32 v11, v11, v28
	ds_bpermute_b32 v28, v9, v11
	s_lshl_b32 s8, s6, 2
	s_add_u32 s8, s72, s8
	s_addc_u32 s9, s73, 0
	s_and_saveexec_b64 s[10:11], vcc
	s_waitcnt lgkmcnt(0)
	v_add_f32_e32 v11, v11, v28
	global_store_dword v10, v11, s[8:9]
	s_or_b64 exec, exec, s[10:11]
	s_add_i32 s6, s6, s70
	s_cmp_lt_i32 s6, 0xc000
	s_cbranch_scc0 .Lnp_done
.Lnp_loop:
	s_add_i32 s92, s6, s70
	s_add_i32 s92, s92, s70
	s_cmp_lt_i32 s92, 0xc000
	s_cbranch_scc0 .Lnp_skip_b2
	s_cmpk_lt_i32 s92, 0x4000
	s_cselect_b32 s94, s52, s54
	s_cselect_b32 s95, s53, s55
	s_cselect_b32 s93, 0, 0x4000
	s_sub_i32 s93, s92, s93
	s_lshl_b32 s93, s93, 12
	s_add_u32 s94, s94, s93
	s_addc_u32 s95, s95, 0
	v_lshl_add_u64 v[28:29], v[0:1], 4, s[94:95]
	global_load_dwordx4 v[56:59], v[28:29], off
	global_load_dwordx4 v[60:63], v[28:29], off offset:1024
	global_load_dwordx4 v[64:67], v[28:29], off offset:2048
	global_load_dwordx4 v[68:71], v[28:29], off offset:3072
	s_waitcnt vmcnt(18)
	s_branch .Lnp_proc_b2

; #define GAS __attribute__((address_space(1)))
; __device__ __forceinline__ unsigned cvt_pk_bf16(float lo, float hi) { f32x2_t v = {lo, hi}; bf16x2_t b = __builtin_convertvector(v, bf16x2_t); return __builtin_bit_cast(unsigned, b); }
; template <bool FIRST>
; __device__ __forceinline__ void norm_phase(const float* xp, const float* xs, float* out, unsigned char* ws, int mode, const float* gain, int gw, int NGW, int lane) {
;     ...
; #pragma unroll
;         for (int j = 0; j < 4; ++j) s += (v[j][0] * v[j][0] + v[j][1] * v[j][1]) + (v[j][2] * v[j][2] + v[j][3] * v[j][3]);
;         s = wave_sum(s);
;         if (!FIRST) {
;             const float rs = __builtin_amdgcn_rsqf(s * (1.0f / 1024.0f) + EPS); float s2 = 0.f;
; #pragma unroll
;             for (int j = 0; j < 4; ++j) { const f32x4 gg = *((const GAS f32x4*)gain + lane + 64 * j); v[j] = v[j] * rs * gg; s2 += (v[j][0] * v[j][0] + v[j][1] * v[j][1]) + (v[j][2] * v[j][2] + v[j][3] * v[j][3]); }
;             s = wave_sum(s2);
;         }
;         if (mode == 2) {
; #pragma unroll
;             for (int j = 0; j < 4; ++j) *((GAS f32x4*)(out + (size_t)m * D) + lane + 64 * j) = v[j];
;         } else {
; #pragma unroll
;             for (int j = 0; j < 4; ++j) { u32x2 w; w.x = cvt_pk_bf16(v[j][0], v[j][1]); w.y = cvt_pk_bf16(v[j][2], v[j][3]); *((GAS u32x2*)(xb + (size_t)m * D) + lane + 64 * j) = w; }
;             if (lane == 0) ss1[m] = s;
.Lnp_proc_b2:
	v_mul_f32_e32 v11, v73, v73
	v_mul_f32_e32 v28, v75, v75
	v_mul_f32_e32 v29, v77, v77
	v_mul_f32_e32 v30, v79, v79
	v_mul_f32_e32 v31, v81, v81
	v_mul_f32_e32 v32, v83, v83
	v_fmac_f32_e32 v11, v72, v72
	v_fmac_f32_e32 v28, v74, v74
	v_fmac_f32_e32 v29, v76, v76
	v_fmac_f32_e32 v30, v78, v78
	v_mul_f32_e32 v33, v85, v85
	v_mul_f32_e32 v34, v87, v87
	v_fmac_f32_e32 v31, v80, v80
	v_fmac_f32_e32 v32, v82, v82
	v_add_f32_e32 v11, v11, v28
	v_add_f32_e32 v28, v29, v30
	v_fmac_f32_e32 v33, v84, v84
	v_fmac_f32_e32 v34, v86, v86
	v_add_f32_e32 v29, v31, v32
	v_add_f32_e32 v11, v11, v28
	v_add_f32_e32 v30, v33, v34
	v_add_f32_e32 v11, v11, v29
	v_add_f32_e32 v11, v11, v30
	ds_bpermute_b32 v28, v4, v11
	v_cvt_pk_bf16_f32 v88, v72, v73
	v_cvt_pk_bf16_f32 v89, v74, v75
	v_cvt_pk_bf16_f32 v90, v76, v77
	v_cvt_pk_bf16_f32 v91, v78, v79
	v_cvt_pk_bf16_f32 v92, v80, v81
	v_cvt_pk_bf16_f32 v93, v82, v83
	v_cvt_pk_bf16_f32 v94, v84, v85
	v_cvt_pk_bf16_f32 v95, v86, v87
	s_lshl_b32 s10, s6, 11
	s_mov_b32 s11, 0
	v_lshl_add_u64 v[30:31], v[2:3], 0, s[10:11]
	global_store_dwordx2 v[30:31], v[88:89], off
	global_store_dwordx2 v[30:31], v[90:91], off offset:512
	global_store_dwordx2 v[30:31], v[92:93], off offset:1024
	global_store_dwordx2 v[30:31], v[94:95], off offset:1536
	s_waitcnt lgkmcnt(0)
	v_add_f32_e32 v11, v11, v28
	ds_bpermute_b32 v28, v5, v11
	s_waitcnt lgkmcnt(0)
	v_add_f32_e32 v11, v11, v28
	ds_bpermute_b32 v28, v6, v11
	s_waitcnt lgkmcnt(0)
	v_add_f32_e32 v11, v11, v28
	ds_bpermute_b32 v28, v7, v11
	s_waitcnt lgkmcnt(0)
	v_add_f32_e32 v11, v11, v28
	ds_bpermute_b32 v28, v8, v11
	s_waitcnt lgkmcnt(0)
	v_add_f32_e32 v11, v11, v28
	ds_bpermute_b32 v28, v9, v11
	s_lshl_b32 s8, s6, 2
	s_add_u32 s8, s72, s8
	s_addc_u32 s9, s73, 0
	s_and_saveexec_b64 s[10:11], vcc
	s_waitcnt lgkmcnt(0)
	v_add_f32_e32 v11, v11, v28
	global_store_dword v10, v11, s[8:9]
	s_or_b64 exec, exec, s[10:11]
	s_add_i32 s6, s6, s70
	s_cmp_lt_i32 s6, 0xc000
	s_cbranch_scc0 .Lnp_done
	s_add_i32 s92, s6, s70
	s_add_i32 s92, s92, s70
	s_cmp_lt_i32 s92, 0xc000
	s_cbranch_scc0 .Lnp_skip_b0
	s_cmpk_lt_i32 s92, 0x4000
	s_cselect_b32 s94, s52, s54
	s_cselect_b32 s95, s53, s55
	s_cselect_b32 s93, 0, 0x4000
	s_sub_i32 s93, s92, s93
	s_lshl_b32 s93, s93, 12
	s_add_u32 s94, s94, s93
	s_addc_u32 s95, s95, 0
	v_lshl_add_u64 v[28:29], v[0:1], 4, s[94:95]
	global_load_dwordx4 v[72:75], v[28:29], off
	global_load_dwordx4 v[76:79], v[28:29], off offset:1024
	global_load_dwordx4 v[80:83], v[28:29], off offset:2048
	global_load_dwordx4 v[84:87], v[28:29], off offset:3072
	s_waitcnt vmcnt(18)
	s_branch .Lnp_proc_b0

; #define GAS __attribute__((address_space(1)))
; __device__ __forceinline__ unsigned cvt_pk_bf16(float lo, float hi) { f32x2_t v = {lo, hi}; bf16x2_t b = __builtin_convertvector(v, bf16x2_t); return __builtin_bit_cast(unsigned, b); }
; template <bool FIRST>
; __device__ __forceinline__ void norm_phase(const float* xp, const float* xs, float* out, unsigned char* ws, int mode, const float* gain, int gw, int NGW, int lane) {
;     ...
; #pragma unroll
;         for (int j = 0; j < 4; ++j) s += (v[j][0] * v[j][0] + v[j][1] * v[j][1]) + (v[j][2] * v[j][2] + v[j][3] * v[j][3]);
;         s = wave_sum(s);
;         if (!FIRST) {
;             const float rs = __builtin_amdgcn_rsqf(s * (1.0f / 1024.0f) + EPS); float s2 = 0.f;
; #pragma unroll
;             for (int j = 0; j < 4; ++j) { const f32x4 gg = *((const GAS f32x4*)gain + lane + 64 * j); v[j] = v[j] * rs * gg; s2 += (v[j][0] * v[j][0] + v[j][1] * v[j][1]) + (v[j][2] * v[j][2] + v[j][3] * v[j][3]); }
;             s = wave_sum(s2);
;         }
;         if (mode == 2) {
; #pragma unroll
;             for (int j = 0; j < 4; ++j) *((GAS f32x4*)(out + (size_t)m * D) + lane + 64 * j) = v[j];
;         } else {
; #pragma unroll
;             for (int j = 0; j < 4; ++j) { u32x2 w; w.x = cvt_pk_bf16(v[j][0], v[j][1]); w.y = cvt_pk_bf16(v[j][2], v[j][3]); *((GAS u32x2*)(xb + (size_t)m * D) + lane + 64 * j) = w; }
;             if (lane == 0) ss1[m] = s;
.Lnp_proc_b0:
	v_mul_f32_e32 v11, v13, v13
	v_mul_f32_e32 v28, v15, v15
	v_mul_f32_e32 v29, v17, v17
	v_mul_f32_e32 v30, v19, v19
	v_mul_f32_e32 v31, v21, v21
	v_mul_f32_e32 v32, v23, v23
	v_fmac_f32_e32 v11, v12, v12
	v_fmac_f32_e32 v28, v14, v14
	v_fmac_f32_e32 v29, v16, v16
	v_fmac_f32_e32 v30, v18, v18
	v_mul_f32_e32 v33, v25, v25
	v_mul_f32_e32 v34, v27, v27
	v_fmac_f32_e32 v31, v20, v20
	v_fmac_f32_e32 v32, v22, v22
	v_add_f32_e32 v11, v11, v28
	v_add_f32_e32 v28, v29, v30
	v_fmac_f32_e32 v33, v24, v24
	v_fmac_f32_e32 v34, v26, v26
	v_add_f32_e32 v29, v31, v32
	v_add_f32_e32 v11, v11, v28
	v_add_f32_e32 v30, v33, v34
	v_add_f32_e32 v11, v11, v29
	v_add_f32_e32 v11, v11, v30
	ds_bpermute_b32 v28, v4, v11
	v_cvt_pk_bf16_f32 v88, v12, v13
	v_cvt_pk_bf16_f32 v89, v14, v15
	v_cvt_pk_bf16_f32 v90, v16, v17
	v_cvt_pk_bf16_f32 v91, v18, v19
	v_cvt_pk_bf16_f32 v92, v20, v21
	v_cvt_pk_bf16_f32 v93, v22, v23
	v_cvt_pk_bf16_f32 v94, v24, v25
	v_cvt_pk_bf16_f32 v95, v26, v27
	s_lshl_b32 s10, s6, 11
	s_mov_b32 s11, 0
	v_lshl_add_u64 v[30:31], v[2:3], 0, s[10:11]
	global_store_dwordx2 v[30:31], v[88:89], off
	global_store_dwordx2 v[30:31], v[90:91], off offset:512
	global_store_dwordx2 v[30:31], v[92:93], off offset:1024
	global_store_dwordx2 v[30:31], v[94:95], off offset:1536
	s_waitcnt lgkmcnt(0)
	v_add_f32_e32 v11, v11, v28
	ds_bpermute_b32 v28, v5, v11
	s_waitcnt lgkmcnt(0)
	v_add_f32_e32 v11, v11, v28
	ds_bpermute_b32 v28, v6, v11
	s_waitcnt lgkmcnt(0)
	v_add_f32_e32 v11, v11, v28
	ds_bpermute_b32 v28, v7, v11
	s_waitcnt lgkmcnt(0)
	v_add_f32_e32 v11, v11, v28
	ds_bpermute_b32 v28, v8, v11
	s_waitcnt lgkmcnt(0)
	v_add_f32_e32 v11, v11, v28
	ds_bpermute_b32 v28, v9, v11
	s_lshl_b32 s8, s6, 2
	s_add_u32 s8, s72, s8
	s_addc_u32 s9, s73, 0
	s_and_saveexec_b64 s[10:11], vcc
	s_waitcnt lgkmcnt(0)
	v_add_f32_e32 v11, v11, v28
	global_store_dword v10, v11, s[8:9]
	s_or_b64 exec, exec, s[10:11]
	s_add_i32 s6, s6, s70
	s_cmp_lt_i32 s6, 0xc000
	s_cbranch_scc0 .Lnp_done
	s_add_i32 s92, s6, s70
	s_add_i32 s92, s92, s70
	s_cmp_lt_i32 s92, 0xc000
	s_cbranch_scc0 .Lnp_skip_b1
	s_cmpk_lt_i32 s92, 0x4000
	s_cselect_b32 s94, s52, s54
	s_cselect_b32 s95, s53, s55
	s_cselect_b32 s93, 0, 0x4000
	s_sub_i32 s93, s92, s93
	s_lshl_b32 s93, s93, 12
	s_add_u32 s94, s94, s93
	s_addc_u32 s95, s95, 0
	v_lshl_add_u64 v[28:29], v[0:1], 4, s[94:95]
	global_load_dwordx4 v[12:15], v[28:29], off
	global_load_dwordx4 v[16:19], v[28:29], off offset:1024
	global_load_dwordx4 v[20:23], v[28:29], off offset:2048
	global_load_dwordx4 v[24:27], v[28:29], off offset:3072
	s_waitcnt vmcnt(18)
	s_branch .Lnp_proc_b1

; #define GAS __attribute__((address_space(1)))
; __device__ __forceinline__ unsigned cvt_pk_bf16(float lo, float hi) { f32x2_t v = {lo, hi}; bf16x2_t b = __builtin_convertvector(v, bf16x2_t); return __builtin_bit_cast(unsigned, b); }
; #define CPY(off, src, n) for (int i = tid; i < (n); i += 512) pw[(off) + i] = (src)[i]
; template <bool FIRST>
; __device__ __forceinline__ void norm_phase(const float* xp, const float* xs, float* out, unsigned char* ws, int mode, const float* gain, int gw, int NGW, int lane) {
;     ...
; #pragma unroll
;         for (int j = 0; j < 4; ++j) s += (v[j][0] * v[j][0] + v[j][1] * v[j][1]) + (v[j][2] * v[j][2] + v[j][3] * v[j][3]);
;         s = wave_sum(s);
;         if (!FIRST) {
;             const float rs = __builtin_amdgcn_rsqf(s * (1.0f / 1024.0f) + EPS); float s2 = 0.f;
; #pragma unroll
;             for (int j = 0; j < 4; ++j) { const f32x4 gg = *((const GAS f32x4*)gain + lane + 64 * j); v[j] = v[j] * rs * gg; s2 += (v[j][0] * v[j][0] + v[j][1] * v[j][1]) + (v[j][2] * v[j][2] + v[j][3] * v[j][3]); }
;             s = wave_sum(s2);
;         }
;         if (mode == 2) {
; #pragma unroll
;             for (int j = 0; j < 4; ++j) *((GAS f32x4*)(out + (size_t)m * D) + lane + 64 * j) = v[j];
;         } else {
; #pragma unroll
;             for (int j = 0; j < 4; ++j) { u32x2 w; w.x = cvt_pk_bf16(v[j][0], v[j][1]); w.y = cvt_pk_bf16(v[j][2], v[j][3]); *((GAS u32x2*)(xb + (size_t)m * D) + lane + 64 * j) = w; }
;             if (lane == 0) ss1[m] = s;
; __global__ void __launch_bounds__(512) mk_fwd(Args a) {
;     ...
;     if (blockIdx.x == 0) {
;         float* pw = (float*)(a.ws + WS_PAR);
;     ...
;         CPY(P_CONV, a.in[7], 2304); CPY(P_DQN, a.in[8], 64); CPY(P_DKN, a.in[9], 64); CPY(P_LQ1, a.in[10], 64); CPY(P_LK1, a.in[11], 64); CPY(P_LQ2, a.in[12], 64); CPY(P_LK2, a.in[13], 64);
.Lnp_proc_b1:
	v_mul_f32_e32 v11, v57, v57
	v_mul_f32_e32 v28, v59, v59
	v_mul_f32_e32 v29, v61, v61
	v_mul_f32_e32 v30, v63, v63
	v_mul_f32_e32 v31, v65, v65
	v_mul_f32_e32 v32, v67, v67
	v_fmac_f32_e32 v11, v56, v56
	v_fmac_f32_e32 v28, v58, v58
	v_fmac_f32_e32 v29, v60, v60
	v_fmac_f32_e32 v30, v62, v62
	v_mul_f32_e32 v33, v69, v69
	v_mul_f32_e32 v34, v71, v71
	v_fmac_f32_e32 v31, v64, v64
	v_fmac_f32_e32 v32, v66, v66
	v_add_f32_e32 v11, v11, v28
	v_add_f32_e32 v28, v29, v30
	v_fmac_f32_e32 v33, v68, v68
	v_fmac_f32_e32 v34, v70, v70
	v_add_f32_e32 v29, v31, v32
	v_add_f32_e32 v11, v11, v28
	v_add_f32_e32 v30, v33, v34
	v_add_f32_e32 v11, v11, v29
	v_add_f32_e32 v11, v11, v30
	ds_bpermute_b32 v28, v4, v11
	v_cvt_pk_bf16_f32 v88, v56, v57
	v_cvt_pk_bf16_f32 v89, v58, v59
	v_cvt_pk_bf16_f32 v90, v60, v61
	v_cvt_pk_bf16_f32 v91, v62, v63
	v_cvt_pk_bf16_f32 v92, v64, v65
	v_cvt_pk_bf16_f32 v93, v66, v67
	v_cvt_pk_bf16_f32 v94, v68, v69
	v_cvt_pk_bf16_f32 v95, v70, v71
	s_lshl_b32 s10, s6, 11
	s_mov_b32 s11, 0
	v_lshl_add_u64 v[30:31], v[2:3], 0, s[10:11]
	global_store_dwordx2 v[30:31], v[88:89], off
	global_store_dwordx2 v[30:31], v[90:91], off offset:512
	global_store_dwordx2 v[30:31], v[92:93], off offset:1024
	global_store_dwordx2 v[30:31], v[94:95], off offset:1536
	s_waitcnt lgkmcnt(0)
	v_add_f32_e32 v11, v11, v28
	ds_bpermute_b32 v28, v5, v11
	s_waitcnt lgkmcnt(0)
	v_add_f32_e32 v11, v11, v28
	ds_bpermute_b32 v28, v6, v11
	s_waitcnt lgkmcnt(0)
	v_add_f32_e32 v11, v11, v28
	ds_bpermute_b32 v28, v7, v11
	s_waitcnt lgkmcnt(0)
	v_add_f32_e32 v11, v11, v28
	ds_bpermute_b32 v28, v8, v11
	s_waitcnt lgkmcnt(0)
	v_add_f32_e32 v11, v11, v28
	ds_bpermute_b32 v28, v9, v11
	s_lshl_b32 s8, s6, 2
	s_add_u32 s8, s72, s8
	s_addc_u32 s9, s73, 0
	s_and_saveexec_b64 s[10:11], vcc
	s_waitcnt lgkmcnt(0)
	v_add_f32_e32 v11, v11, v28
	global_store_dword v10, v11, s[8:9]
	s_or_b64 exec, exec, s[10:11]
	s_add_i32 s6, s6, s70
	s_cmp_lt_i32 s6, 0xc000
	s_cbranch_scc0 .Lnp_done
	s_branch .Lnp_loop
.Lnp_done:
.LBB0_97:
	s_cmp_lg_u32 s14, 0
	s_cbranch_scc1 .LBB0_109
	v_mov_b32_e32 v3, 0
	v_lshlrev_b32_e32 v2, 2, v154
	v_add_u32_e32 v8, 0xfffffe00, v154
	v_lshl_add_u64 v[4:5], s[72:73], 0, v[2:3]
	s_mov_b64 s[0:1], 0xc0000
	v_lshl_add_u64 v[0:1], s[66:67], 0, v[2:3]
	v_lshl_add_u64 v[6:7], v[4:5], 0, s[0:1]
	s_mov_b64 s[0:1], 0
	s_mov_b64 s[2:3], 0x800
	s_movk_i32 s4, 0x6ff
	v_mov_b32_e32 v9, v8
